# c20: c16 + FFN-in SwiGLU epilogues: 7 of 8 per-piece 64-bit address chains folded into store offset immediates off two derived bases (35 VALU ops -> 2 per wave and unit)
# baseline (speedup 1.0000x reference)
.LBB0_347:
	v_exp_f32_e32 v150, v126
	v_exp_f32_e32 v152, v122
	v_exp_f32_e32 v151, v127
	v_exp_f32_e32 v156, v124
	v_exp_f32_e32 v157, v125
	v_exp_f32_e32 v153, v123
	v_exp_f32_e32 v154, v128
	v_exp_f32_e32 v155, v129
	s_lshl_b32 s9, s17, 1
	v_pk_add_f32 v[150:151], v[150:151], 1.0 op_sel_hi:[1,0]
	v_pk_add_f32 v[156:157], v[156:157], 1.0 op_sel_hi:[1,0]
	v_pk_add_f32 v[152:153], v[152:153], 1.0 op_sel_hi:[1,0]
	v_lshl_add_u32 v136, s16, 8, v142
	s_or_b32 s16, s9, s66
	v_rcp_f32_e32 v150, v150
	v_rcp_f32_e32 v152, v152
	v_rcp_f32_e32 v151, v151
	v_rcp_f32_e32 v153, v153
	v_rcp_f32_e32 v156, v156
	v_rcp_f32_e32 v157, v157
	s_ashr_i32 s17, s16, 31
	v_pk_add_f32 v[154:155], v[154:155], 1.0 op_sel_hi:[1,0]
	s_lshl_b64 s[16:17], s[16:17], 14
	v_ashrrev_i32_e32 v137, 31, v136
	v_rcp_f32_e32 v154, v154
	v_rcp_f32_e32 v155, v155
	s_mov_b32 s98, 0x1000
	s_mov_b32 s99, 0
	s_mov_b32 s100, 0x4c00
	s_mov_b32 s101, 0
	v_lshl_add_u64 v[148:149], s[16:17], 0, v[136:137]
	v_pk_mul_f32 v[118:119], v[126:127], v[118:119]
	v_pk_mul_f32 v[116:117], v[124:125], v[116:117]
	v_pk_mul_f32 v[114:115], v[122:123], v[114:115]
	v_lshlrev_b64 v[148:149], 7, v[148:149]
	v_pk_mul_f32 v[118:119], v[150:151], v[118:119]
	v_pk_mul_f32 v[122:123], v[156:157], v[116:117]
	v_pk_mul_f32 v[116:117], v[152:153], v[114:115]
	v_lshl_add_u64 v[148:149], v[130:131], 0, v[148:149]
	v_lshl_add_u64 v[252:253], v[148:149], 0, s[98:99]
	v_lshl_add_u64 v[254:255], v[148:149], 0, s[100:101]
	v_pk_mul_f32 v[120:121], v[128:129], v[120:121]
	v_cvt_pk_bf16_f32 v114, v118, v119
	v_cvt_pk_bf16_f32 v116, v116, v117
	v_cvt_pk_bf16_f32 v117, v122, v123
	v_exp_f32_e32 v118, v106
	v_exp_f32_e32 v122, v108
	v_exp_f32_e32 v123, v109
	v_exp_f32_e32 v119, v107
	v_pk_mul_f32 v[120:121], v[154:155], v[120:121]
	v_pk_mul_f32 v[100:101], v[108:109], v[100:101]
	v_cvt_pk_bf16_f32 v115, v120, v121
	global_store_dwordx4 v[148:149], v[114:117], off
	v_exp_f32_e32 v120, v112
	v_exp_f32_e32 v121, v113
	v_exp_f32_e32 v116, v110
	v_exp_f32_e32 v117, v111
	v_pk_add_f32 v[122:123], v[122:123], 1.0 op_sel_hi:[1,0]
	v_pk_add_f32 v[118:119], v[118:119], 1.0 op_sel_hi:[1,0]
	v_rcp_f32_e32 v122, v122
	v_pk_add_f32 v[116:117], v[116:117], 1.0 op_sel_hi:[1,0]
	v_rcp_f32_e32 v118, v118
	v_rcp_f32_e32 v119, v119
	v_rcp_f32_e32 v123, v123
	v_pk_add_f32 v[120:121], v[120:121], 1.0 op_sel_hi:[1,0]
	v_rcp_f32_e32 v116, v116
	v_rcp_f32_e32 v117, v117
	v_rcp_f32_e32 v120, v120
	v_rcp_f32_e32 v121, v121
	v_pk_mul_f32 v[98:99], v[106:107], v[98:99]
	v_pk_mul_f32 v[102:103], v[110:111], v[102:103]
	v_pk_mul_f32 v[106:107], v[122:123], v[100:101]
	v_pk_mul_f32 v[100:101], v[118:119], v[98:99]
	v_pk_mul_f32 v[104:105], v[112:113], v[104:105]
	v_pk_mul_f32 v[102:103], v[116:117], v[102:103]
	v_cvt_pk_bf16_f32 v100, v100, v101
	v_cvt_pk_bf16_f32 v101, v106, v107
	v_pk_mul_f32 v[104:105], v[120:121], v[104:105]
	v_cvt_pk_bf16_f32 v98, v102, v103
	v_exp_f32_e32 v102, v90
	v_cvt_pk_bf16_f32 v99, v104, v105
	global_store_dwordx4 v[252:253], v[98:101], off offset:-2048
	v_exp_f32_e32 v106, v92
	v_exp_f32_e32 v107, v93
	v_exp_f32_e32 v100, v94
	v_exp_f32_e32 v101, v95
	v_exp_f32_e32 v103, v91
	v_exp_f32_e32 v104, v96
	v_exp_f32_e32 v105, v97
	v_pk_add_f32 v[100:101], v[100:101], 1.0 op_sel_hi:[1,0]
	v_pk_add_f32 v[106:107], v[106:107], 1.0 op_sel_hi:[1,0]
	v_pk_add_f32 v[102:103], v[102:103], 1.0 op_sel_hi:[1,0]
	v_rcp_f32_e32 v100, v100
	v_rcp_f32_e32 v102, v102
	v_rcp_f32_e32 v101, v101
	v_rcp_f32_e32 v103, v103
	v_rcp_f32_e32 v106, v106
	v_rcp_f32_e32 v107, v107
	v_pk_add_f32 v[104:105], v[104:105], 1.0 op_sel_hi:[1,0]
	v_rcp_f32_e32 v104, v104
	v_rcp_f32_e32 v105, v105
	v_pk_mul_f32 v[86:87], v[94:95], v[86:87]
	v_pk_mul_f32 v[84:85], v[92:93], v[84:85]
	v_pk_mul_f32 v[82:83], v[90:91], v[82:83]
	v_pk_mul_f32 v[86:87], v[100:101], v[86:87]
	v_pk_mul_f32 v[90:91], v[106:107], v[84:85]
	v_pk_mul_f32 v[84:85], v[102:103], v[82:83]
	v_pk_mul_f32 v[88:89], v[96:97], v[88:89]
	v_cvt_pk_bf16_f32 v82, v86, v87
	v_cvt_pk_bf16_f32 v84, v84, v85
	v_cvt_pk_bf16_f32 v85, v90, v91
	v_exp_f32_e32 v86, v74
	v_exp_f32_e32 v90, v76
	v_exp_f32_e32 v91, v77
	v_exp_f32_e32 v87, v75
	v_pk_mul_f32 v[88:89], v[104:105], v[88:89]
	v_pk_mul_f32 v[68:69], v[76:77], v[68:69]
	v_cvt_pk_bf16_f32 v83, v88, v89
	global_store_dwordx4 v[252:253], v[82:85], off
	v_exp_f32_e32 v88, v80
	v_exp_f32_e32 v89, v81
	v_exp_f32_e32 v84, v78
	v_exp_f32_e32 v85, v79
	v_pk_add_f32 v[90:91], v[90:91], 1.0 op_sel_hi:[1,0]
	v_pk_add_f32 v[86:87], v[86:87], 1.0 op_sel_hi:[1,0]
	v_rcp_f32_e32 v90, v90
	v_pk_add_f32 v[84:85], v[84:85], 1.0 op_sel_hi:[1,0]
	v_rcp_f32_e32 v86, v86
	v_rcp_f32_e32 v87, v87
	v_rcp_f32_e32 v91, v91
	v_pk_add_f32 v[88:89], v[88:89], 1.0 op_sel_hi:[1,0]
	v_rcp_f32_e32 v84, v84
	v_rcp_f32_e32 v85, v85
	v_rcp_f32_e32 v88, v88
	v_rcp_f32_e32 v89, v89
	v_pk_mul_f32 v[66:67], v[74:75], v[66:67]
	v_pk_mul_f32 v[70:71], v[78:79], v[70:71]
	v_pk_mul_f32 v[74:75], v[90:91], v[68:69]
	v_pk_mul_f32 v[68:69], v[86:87], v[66:67]
	v_pk_mul_f32 v[72:73], v[80:81], v[72:73]
	v_pk_mul_f32 v[70:71], v[84:85], v[70:71]
	v_cvt_pk_bf16_f32 v68, v68, v69
	v_cvt_pk_bf16_f32 v69, v74, v75
	v_pk_mul_f32 v[72:73], v[88:89], v[72:73]
	v_cvt_pk_bf16_f32 v66, v70, v71
	v_exp_f32_e32 v70, v58
	v_cvt_pk_bf16_f32 v67, v72, v73
	global_store_dwordx4 v[252:253], v[66:69], off offset:2048
	v_exp_f32_e32 v74, v60
	v_exp_f32_e32 v75, v61
	v_exp_f32_e32 v68, v62
	v_exp_f32_e32 v69, v63
	v_exp_f32_e32 v71, v59
	v_exp_f32_e32 v72, v64
	v_exp_f32_e32 v73, v65
	v_pk_add_f32 v[68:69], v[68:69], 1.0 op_sel_hi:[1,0]
	v_pk_add_f32 v[74:75], v[74:75], 1.0 op_sel_hi:[1,0]
	v_pk_add_f32 v[70:71], v[70:71], 1.0 op_sel_hi:[1,0]
	v_rcp_f32_e32 v68, v68
	v_rcp_f32_e32 v70, v70
	v_rcp_f32_e32 v69, v69
	v_rcp_f32_e32 v71, v71
	v_rcp_f32_e32 v74, v74
	v_rcp_f32_e32 v75, v75
	v_pk_add_f32 v[72:73], v[72:73], 1.0 op_sel_hi:[1,0]
	v_rcp_f32_e32 v72, v72
	v_rcp_f32_e32 v73, v73
	v_pk_mul_f32 v[54:55], v[62:63], v[54:55]
	v_pk_mul_f32 v[52:53], v[60:61], v[52:53]
	v_pk_mul_f32 v[50:51], v[58:59], v[50:51]
	v_pk_mul_f32 v[54:55], v[68:69], v[54:55]
	v_pk_mul_f32 v[58:59], v[74:75], v[52:53]
	v_pk_mul_f32 v[52:53], v[70:71], v[50:51]
	v_pk_mul_f32 v[56:57], v[64:65], v[56:57]
	v_cvt_pk_bf16_f32 v50, v54, v55
	v_cvt_pk_bf16_f32 v52, v52, v53
	v_cvt_pk_bf16_f32 v53, v58, v59
	v_exp_f32_e32 v54, v42
	v_exp_f32_e32 v58, v44
	v_exp_f32_e32 v59, v45
	v_exp_f32_e32 v55, v43
	v_pk_mul_f32 v[56:57], v[72:73], v[56:57]
	v_pk_mul_f32 v[36:37], v[44:45], v[36:37]
	v_cvt_pk_bf16_f32 v51, v56, v57
	global_store_dwordx4 v[254:255], v[50:53], off offset:-3072
	v_exp_f32_e32 v56, v48
	v_exp_f32_e32 v57, v49
	v_exp_f32_e32 v52, v46
	v_exp_f32_e32 v53, v47
	v_pk_add_f32 v[58:59], v[58:59], 1.0 op_sel_hi:[1,0]
	v_pk_add_f32 v[54:55], v[54:55], 1.0 op_sel_hi:[1,0]
	v_rcp_f32_e32 v58, v58
	v_pk_add_f32 v[52:53], v[52:53], 1.0 op_sel_hi:[1,0]
	v_rcp_f32_e32 v54, v54
	v_rcp_f32_e32 v55, v55
	v_rcp_f32_e32 v59, v59
	v_pk_add_f32 v[56:57], v[56:57], 1.0 op_sel_hi:[1,0]
	v_rcp_f32_e32 v52, v52
	v_rcp_f32_e32 v53, v53
	v_rcp_f32_e32 v56, v56
	v_rcp_f32_e32 v57, v57
	v_pk_mul_f32 v[34:35], v[42:43], v[34:35]
	v_pk_mul_f32 v[38:39], v[46:47], v[38:39]
	v_pk_mul_f32 v[42:43], v[58:59], v[36:37]
	v_pk_mul_f32 v[36:37], v[54:55], v[34:35]
	v_pk_mul_f32 v[40:41], v[48:49], v[40:41]
	v_pk_mul_f32 v[38:39], v[52:53], v[38:39]
	v_cvt_pk_bf16_f32 v36, v36, v37
	v_cvt_pk_bf16_f32 v37, v42, v43
	v_pk_mul_f32 v[40:41], v[56:57], v[40:41]
	v_cvt_pk_bf16_f32 v34, v38, v39
	v_exp_f32_e32 v38, v26
	v_cvt_pk_bf16_f32 v35, v40, v41
	global_store_dwordx4 v[254:255], v[34:37], off offset:-1024
	v_exp_f32_e32 v42, v28
	v_exp_f32_e32 v43, v29
	v_exp_f32_e32 v36, v30
	v_exp_f32_e32 v37, v31
	v_exp_f32_e32 v39, v27
	v_exp_f32_e32 v40, v32
	v_exp_f32_e32 v41, v33
	v_pk_add_f32 v[36:37], v[36:37], 1.0 op_sel_hi:[1,0]
	v_pk_add_f32 v[42:43], v[42:43], 1.0 op_sel_hi:[1,0]
	v_pk_add_f32 v[38:39], v[38:39], 1.0 op_sel_hi:[1,0]
	v_pk_add_f32 v[40:41], v[40:41], 1.0 op_sel_hi:[1,0]
	v_rcp_f32_e32 v36, v36
	v_rcp_f32_e32 v38, v38
	v_rcp_f32_e32 v37, v37
	v_rcp_f32_e32 v39, v39
	v_rcp_f32_e32 v42, v42
	v_rcp_f32_e32 v43, v43
	v_rcp_f32_e32 v40, v40
	v_rcp_f32_e32 v41, v41
	v_pk_mul_f32 v[22:23], v[30:31], v[22:23]
	v_pk_mul_f32 v[20:21], v[28:29], v[20:21]
	v_pk_mul_f32 v[18:19], v[26:27], v[18:19]
	v_pk_mul_f32 v[24:25], v[32:33], v[24:25]
	v_pk_mul_f32 v[22:23], v[36:37], v[22:23]
	v_pk_mul_f32 v[26:27], v[42:43], v[20:21]
	v_pk_mul_f32 v[20:21], v[38:39], v[18:19]
	v_pk_mul_f32 v[24:25], v[40:41], v[24:25]
	v_cvt_pk_bf16_f32 v18, v22, v23
	v_cvt_pk_bf16_f32 v20, v20, v21
	v_cvt_pk_bf16_f32 v21, v26, v27
	v_exp_f32_e32 v22, v10
	v_exp_f32_e32 v26, v12
	v_exp_f32_e32 v27, v13
	v_exp_f32_e32 v23, v11
	v_cvt_pk_bf16_f32 v19, v24, v25
	global_store_dwordx4 v[254:255], v[18:21], off offset:1024
	v_exp_f32_e32 v24, v16
	v_exp_f32_e32 v25, v17
	v_exp_f32_e32 v20, v14
	v_exp_f32_e32 v21, v15
	v_pk_add_f32 v[26:27], v[26:27], 1.0 op_sel_hi:[1,0]
	v_pk_add_f32 v[22:23], v[22:23], 1.0 op_sel_hi:[1,0]
	v_pk_add_f32 v[24:25], v[24:25], 1.0 op_sel_hi:[1,0]
	v_pk_add_f32 v[20:21], v[20:21], 1.0 op_sel_hi:[1,0]
	v_rcp_f32_e32 v22, v22
	v_rcp_f32_e32 v23, v23
	v_rcp_f32_e32 v26, v26
	v_rcp_f32_e32 v27, v27
	v_rcp_f32_e32 v20, v20
	v_rcp_f32_e32 v21, v21
	v_rcp_f32_e32 v24, v24
	v_rcp_f32_e32 v25, v25
	v_pk_mul_f32 v[4:5], v[12:13], v[4:5]
	v_pk_mul_f32 v[2:3], v[10:11], v[2:3]
	v_pk_mul_f32 v[8:9], v[16:17], v[8:9]
	v_pk_mul_f32 v[6:7], v[14:15], v[6:7]
	v_pk_mul_f32 v[10:11], v[26:27], v[4:5]
	v_pk_mul_f32 v[4:5], v[22:23], v[2:3]
	s_andn2_b64 vcc, exec, s[2:3]
	s_mov_b64 s[2:3], -1
	v_pk_mul_f32 v[8:9], v[24:25], v[8:9]
	v_pk_mul_f32 v[6:7], v[20:21], v[6:7]
	v_cvt_pk_bf16_f32 v3, v8, v9
	v_cvt_pk_bf16_f32 v4, v4, v5
	v_cvt_pk_bf16_f32 v5, v10, v11
	s_nop 0
	v_cvt_pk_bf16_f32 v2, v6, v7
	global_store_dwordx4 v[254:255], v[2:5], off offset:3072
	s_cbranch_vccnz .LBB0_340
	s_andn2_b64 vcc, exec, s[4:5]
	s_cbranch_vccnz .LBB0_339
	s_barrier
	s_branch .LBB0_339

.LBB0_1227:
	v_exp_f32_e32 v150, v126
	v_exp_f32_e32 v152, v122
	v_exp_f32_e32 v151, v127
	v_exp_f32_e32 v156, v124
	v_exp_f32_e32 v157, v125
	v_exp_f32_e32 v153, v123
	v_exp_f32_e32 v154, v128
	v_exp_f32_e32 v155, v129
	s_lshl_b32 s9, s17, 1
	v_pk_add_f32 v[150:151], v[150:151], 1.0 op_sel_hi:[1,0]
	v_pk_add_f32 v[156:157], v[156:157], 1.0 op_sel_hi:[1,0]
	v_pk_add_f32 v[152:153], v[152:153], 1.0 op_sel_hi:[1,0]
	v_lshl_add_u32 v136, s16, 8, v142
	s_or_b32 s16, s9, s58
	v_rcp_f32_e32 v150, v150
	v_rcp_f32_e32 v152, v152
	v_rcp_f32_e32 v151, v151
	v_rcp_f32_e32 v153, v153
	v_rcp_f32_e32 v156, v156
	v_rcp_f32_e32 v157, v157
	s_ashr_i32 s17, s16, 31
	v_pk_add_f32 v[154:155], v[154:155], 1.0 op_sel_hi:[1,0]
	s_lshl_b64 s[16:17], s[16:17], 14
	v_ashrrev_i32_e32 v137, 31, v136
	v_rcp_f32_e32 v154, v154
	v_rcp_f32_e32 v155, v155
	s_mov_b32 s98, 0x1000
	s_mov_b32 s99, 0
	s_mov_b32 s100, 0x4c00
	s_mov_b32 s101, 0
	v_lshl_add_u64 v[148:149], s[16:17], 0, v[136:137]
	v_pk_mul_f32 v[118:119], v[126:127], v[118:119]
	v_pk_mul_f32 v[116:117], v[124:125], v[116:117]
	v_pk_mul_f32 v[114:115], v[122:123], v[114:115]
	v_lshlrev_b64 v[148:149], 7, v[148:149]
	v_pk_mul_f32 v[118:119], v[150:151], v[118:119]
	v_pk_mul_f32 v[122:123], v[156:157], v[116:117]
	v_pk_mul_f32 v[116:117], v[152:153], v[114:115]
	v_lshl_add_u64 v[148:149], v[130:131], 0, v[148:149]
	v_lshl_add_u64 v[252:253], v[148:149], 0, s[98:99]
	v_lshl_add_u64 v[254:255], v[148:149], 0, s[100:101]
	v_pk_mul_f32 v[120:121], v[128:129], v[120:121]
	v_cvt_pk_bf16_f32 v114, v118, v119
	v_cvt_pk_bf16_f32 v116, v116, v117
	v_cvt_pk_bf16_f32 v117, v122, v123
	v_exp_f32_e32 v118, v106
	v_exp_f32_e32 v122, v108
	v_exp_f32_e32 v123, v109
	v_exp_f32_e32 v119, v107
	v_pk_mul_f32 v[120:121], v[154:155], v[120:121]
	v_pk_mul_f32 v[100:101], v[108:109], v[100:101]
	v_cvt_pk_bf16_f32 v115, v120, v121
	global_store_dwordx4 v[148:149], v[114:117], off
	v_exp_f32_e32 v120, v112
	v_exp_f32_e32 v121, v113
	v_exp_f32_e32 v116, v110
	v_exp_f32_e32 v117, v111
	v_pk_add_f32 v[122:123], v[122:123], 1.0 op_sel_hi:[1,0]
	v_pk_add_f32 v[118:119], v[118:119], 1.0 op_sel_hi:[1,0]
	v_rcp_f32_e32 v122, v122
	v_pk_add_f32 v[116:117], v[116:117], 1.0 op_sel_hi:[1,0]
	v_rcp_f32_e32 v118, v118
	v_rcp_f32_e32 v119, v119
	v_rcp_f32_e32 v123, v123
	v_pk_add_f32 v[120:121], v[120:121], 1.0 op_sel_hi:[1,0]
	v_rcp_f32_e32 v116, v116
	v_rcp_f32_e32 v117, v117
	v_rcp_f32_e32 v120, v120
	v_rcp_f32_e32 v121, v121
	v_pk_mul_f32 v[98:99], v[106:107], v[98:99]
	v_pk_mul_f32 v[102:103], v[110:111], v[102:103]
	v_pk_mul_f32 v[106:107], v[122:123], v[100:101]
	v_pk_mul_f32 v[100:101], v[118:119], v[98:99]
	v_pk_mul_f32 v[104:105], v[112:113], v[104:105]
	v_pk_mul_f32 v[102:103], v[116:117], v[102:103]
	v_cvt_pk_bf16_f32 v100, v100, v101
	v_cvt_pk_bf16_f32 v101, v106, v107
	v_pk_mul_f32 v[104:105], v[120:121], v[104:105]
	v_cvt_pk_bf16_f32 v98, v102, v103
	v_exp_f32_e32 v102, v90
	v_cvt_pk_bf16_f32 v99, v104, v105
	global_store_dwordx4 v[252:253], v[98:101], off offset:-2048
	v_exp_f32_e32 v106, v92
	v_exp_f32_e32 v107, v93
	v_exp_f32_e32 v100, v94
	v_exp_f32_e32 v101, v95
	v_exp_f32_e32 v103, v91
	v_exp_f32_e32 v104, v96
	v_exp_f32_e32 v105, v97
	v_pk_add_f32 v[100:101], v[100:101], 1.0 op_sel_hi:[1,0]
	v_pk_add_f32 v[106:107], v[106:107], 1.0 op_sel_hi:[1,0]
	v_pk_add_f32 v[102:103], v[102:103], 1.0 op_sel_hi:[1,0]
	v_rcp_f32_e32 v100, v100
	v_rcp_f32_e32 v102, v102
	v_rcp_f32_e32 v101, v101
	v_rcp_f32_e32 v103, v103
	v_rcp_f32_e32 v106, v106
	v_rcp_f32_e32 v107, v107
	v_pk_add_f32 v[104:105], v[104:105], 1.0 op_sel_hi:[1,0]
	v_rcp_f32_e32 v104, v104
	v_rcp_f32_e32 v105, v105
	v_pk_mul_f32 v[86:87], v[94:95], v[86:87]
	v_pk_mul_f32 v[84:85], v[92:93], v[84:85]
	v_pk_mul_f32 v[82:83], v[90:91], v[82:83]
	v_pk_mul_f32 v[86:87], v[100:101], v[86:87]
	v_pk_mul_f32 v[90:91], v[106:107], v[84:85]
	v_pk_mul_f32 v[84:85], v[102:103], v[82:83]
	v_pk_mul_f32 v[88:89], v[96:97], v[88:89]
	v_cvt_pk_bf16_f32 v82, v86, v87
	v_cvt_pk_bf16_f32 v84, v84, v85
	v_cvt_pk_bf16_f32 v85, v90, v91
	v_exp_f32_e32 v86, v74
	v_exp_f32_e32 v90, v76
	v_exp_f32_e32 v91, v77
	v_exp_f32_e32 v87, v75
	v_pk_mul_f32 v[88:89], v[104:105], v[88:89]
	v_pk_mul_f32 v[68:69], v[76:77], v[68:69]
	v_cvt_pk_bf16_f32 v83, v88, v89
	global_store_dwordx4 v[252:253], v[82:85], off
	v_exp_f32_e32 v88, v80
	v_exp_f32_e32 v89, v81
	v_exp_f32_e32 v84, v78
	v_exp_f32_e32 v85, v79
	v_pk_add_f32 v[90:91], v[90:91], 1.0 op_sel_hi:[1,0]
	v_pk_add_f32 v[86:87], v[86:87], 1.0 op_sel_hi:[1,0]
	v_rcp_f32_e32 v90, v90
	v_pk_add_f32 v[84:85], v[84:85], 1.0 op_sel_hi:[1,0]
	v_rcp_f32_e32 v86, v86
	v_rcp_f32_e32 v87, v87
	v_rcp_f32_e32 v91, v91
	v_pk_add_f32 v[88:89], v[88:89], 1.0 op_sel_hi:[1,0]
	v_rcp_f32_e32 v84, v84
	v_rcp_f32_e32 v85, v85
	v_rcp_f32_e32 v88, v88
	v_rcp_f32_e32 v89, v89
	v_pk_mul_f32 v[66:67], v[74:75], v[66:67]
	v_pk_mul_f32 v[70:71], v[78:79], v[70:71]
	v_pk_mul_f32 v[74:75], v[90:91], v[68:69]
	v_pk_mul_f32 v[68:69], v[86:87], v[66:67]
	v_pk_mul_f32 v[72:73], v[80:81], v[72:73]
	v_pk_mul_f32 v[70:71], v[84:85], v[70:71]
	v_cvt_pk_bf16_f32 v68, v68, v69
	v_cvt_pk_bf16_f32 v69, v74, v75
	v_pk_mul_f32 v[72:73], v[88:89], v[72:73]
	v_cvt_pk_bf16_f32 v66, v70, v71
	v_exp_f32_e32 v70, v58
	v_cvt_pk_bf16_f32 v67, v72, v73
	global_store_dwordx4 v[252:253], v[66:69], off offset:2048
	v_exp_f32_e32 v74, v60
	v_exp_f32_e32 v75, v61
	v_exp_f32_e32 v68, v62
	v_exp_f32_e32 v69, v63
	v_exp_f32_e32 v71, v59
	v_exp_f32_e32 v72, v64
	v_exp_f32_e32 v73, v65
	v_pk_add_f32 v[68:69], v[68:69], 1.0 op_sel_hi:[1,0]
	v_pk_add_f32 v[74:75], v[74:75], 1.0 op_sel_hi:[1,0]
	v_pk_add_f32 v[70:71], v[70:71], 1.0 op_sel_hi:[1,0]
	v_rcp_f32_e32 v68, v68
	v_rcp_f32_e32 v70, v70
	v_rcp_f32_e32 v69, v69
	v_rcp_f32_e32 v71, v71
	v_rcp_f32_e32 v74, v74
	v_rcp_f32_e32 v75, v75
	v_pk_add_f32 v[72:73], v[72:73], 1.0 op_sel_hi:[1,0]
	v_rcp_f32_e32 v72, v72
	v_rcp_f32_e32 v73, v73
	v_pk_mul_f32 v[54:55], v[62:63], v[54:55]
	v_pk_mul_f32 v[52:53], v[60:61], v[52:53]
	v_pk_mul_f32 v[50:51], v[58:59], v[50:51]
	v_pk_mul_f32 v[54:55], v[68:69], v[54:55]
	v_pk_mul_f32 v[58:59], v[74:75], v[52:53]
	v_pk_mul_f32 v[52:53], v[70:71], v[50:51]
	v_pk_mul_f32 v[56:57], v[64:65], v[56:57]
	v_cvt_pk_bf16_f32 v50, v54, v55
	v_cvt_pk_bf16_f32 v52, v52, v53
	v_cvt_pk_bf16_f32 v53, v58, v59
	v_exp_f32_e32 v54, v42
	v_exp_f32_e32 v58, v44
	v_exp_f32_e32 v59, v45
	v_exp_f32_e32 v55, v43
	v_pk_mul_f32 v[56:57], v[72:73], v[56:57]
	v_pk_mul_f32 v[36:37], v[44:45], v[36:37]
	v_cvt_pk_bf16_f32 v51, v56, v57
	global_store_dwordx4 v[254:255], v[50:53], off offset:-3072
	v_exp_f32_e32 v56, v48
	v_exp_f32_e32 v57, v49
	v_exp_f32_e32 v52, v46
	v_exp_f32_e32 v53, v47
	v_pk_add_f32 v[58:59], v[58:59], 1.0 op_sel_hi:[1,0]
	v_pk_add_f32 v[54:55], v[54:55], 1.0 op_sel_hi:[1,0]
	v_rcp_f32_e32 v58, v58
	v_pk_add_f32 v[52:53], v[52:53], 1.0 op_sel_hi:[1,0]
	v_rcp_f32_e32 v54, v54
	v_rcp_f32_e32 v55, v55
	v_rcp_f32_e32 v59, v59
	v_pk_add_f32 v[56:57], v[56:57], 1.0 op_sel_hi:[1,0]
	v_rcp_f32_e32 v52, v52
	v_rcp_f32_e32 v53, v53
	v_rcp_f32_e32 v56, v56
	v_rcp_f32_e32 v57, v57
	v_pk_mul_f32 v[34:35], v[42:43], v[34:35]
	v_pk_mul_f32 v[38:39], v[46:47], v[38:39]
	v_pk_mul_f32 v[42:43], v[58:59], v[36:37]
	v_pk_mul_f32 v[36:37], v[54:55], v[34:35]
	v_pk_mul_f32 v[40:41], v[48:49], v[40:41]
	v_pk_mul_f32 v[38:39], v[52:53], v[38:39]
	v_cvt_pk_bf16_f32 v36, v36, v37
	v_cvt_pk_bf16_f32 v37, v42, v43
	v_pk_mul_f32 v[40:41], v[56:57], v[40:41]
	v_cvt_pk_bf16_f32 v34, v38, v39
	v_exp_f32_e32 v38, v26
	v_cvt_pk_bf16_f32 v35, v40, v41
	global_store_dwordx4 v[254:255], v[34:37], off offset:-1024
	v_exp_f32_e32 v42, v28
	v_exp_f32_e32 v43, v29
	v_exp_f32_e32 v36, v30
	v_exp_f32_e32 v37, v31
	v_exp_f32_e32 v39, v27
	v_exp_f32_e32 v40, v32
	v_exp_f32_e32 v41, v33
	v_pk_add_f32 v[36:37], v[36:37], 1.0 op_sel_hi:[1,0]
	v_pk_add_f32 v[42:43], v[42:43], 1.0 op_sel_hi:[1,0]
	v_pk_add_f32 v[38:39], v[38:39], 1.0 op_sel_hi:[1,0]
	v_pk_add_f32 v[40:41], v[40:41], 1.0 op_sel_hi:[1,0]
	v_rcp_f32_e32 v36, v36
	v_rcp_f32_e32 v38, v38
	v_rcp_f32_e32 v37, v37
	v_rcp_f32_e32 v39, v39
	v_rcp_f32_e32 v42, v42
	v_rcp_f32_e32 v43, v43
	v_rcp_f32_e32 v40, v40
	v_rcp_f32_e32 v41, v41
	v_pk_mul_f32 v[22:23], v[30:31], v[22:23]
	v_pk_mul_f32 v[20:21], v[28:29], v[20:21]
	v_pk_mul_f32 v[18:19], v[26:27], v[18:19]
	v_pk_mul_f32 v[24:25], v[32:33], v[24:25]
	v_pk_mul_f32 v[22:23], v[36:37], v[22:23]
	v_pk_mul_f32 v[26:27], v[42:43], v[20:21]
	v_pk_mul_f32 v[20:21], v[38:39], v[18:19]
	v_pk_mul_f32 v[24:25], v[40:41], v[24:25]
	v_cvt_pk_bf16_f32 v18, v22, v23
	v_cvt_pk_bf16_f32 v20, v20, v21
	v_cvt_pk_bf16_f32 v21, v26, v27
	v_exp_f32_e32 v22, v10
	v_exp_f32_e32 v26, v12
	v_exp_f32_e32 v27, v13
	v_exp_f32_e32 v23, v11
	v_cvt_pk_bf16_f32 v19, v24, v25
	global_store_dwordx4 v[254:255], v[18:21], off offset:1024
	v_exp_f32_e32 v24, v16
	v_exp_f32_e32 v25, v17
	v_exp_f32_e32 v20, v14
	v_exp_f32_e32 v21, v15
	v_pk_add_f32 v[26:27], v[26:27], 1.0 op_sel_hi:[1,0]
	v_pk_add_f32 v[22:23], v[22:23], 1.0 op_sel_hi:[1,0]
	v_pk_add_f32 v[24:25], v[24:25], 1.0 op_sel_hi:[1,0]
	v_pk_add_f32 v[20:21], v[20:21], 1.0 op_sel_hi:[1,0]
	v_rcp_f32_e32 v22, v22
	v_rcp_f32_e32 v23, v23
	v_rcp_f32_e32 v26, v26
	v_rcp_f32_e32 v27, v27
	v_rcp_f32_e32 v20, v20
	v_rcp_f32_e32 v21, v21
	v_rcp_f32_e32 v24, v24
	v_rcp_f32_e32 v25, v25
	v_pk_mul_f32 v[4:5], v[12:13], v[4:5]
	v_pk_mul_f32 v[2:3], v[10:11], v[2:3]
	v_pk_mul_f32 v[8:9], v[16:17], v[8:9]
	v_pk_mul_f32 v[6:7], v[14:15], v[6:7]
	v_pk_mul_f32 v[10:11], v[26:27], v[4:5]
	v_pk_mul_f32 v[4:5], v[22:23], v[2:3]
	s_andn2_b64 vcc, exec, s[2:3]
	s_mov_b64 s[2:3], -1
	v_pk_mul_f32 v[8:9], v[24:25], v[8:9]
	v_pk_mul_f32 v[6:7], v[20:21], v[6:7]
	v_cvt_pk_bf16_f32 v3, v8, v9
	v_cvt_pk_bf16_f32 v4, v4, v5
	v_cvt_pk_bf16_f32 v5, v10, v11
	s_nop 0
	v_cvt_pk_bf16_f32 v2, v6, v7
	global_store_dwordx4 v[254:255], v[2:5], off offset:3072
	s_cbranch_vccnz .LBB0_1220
	s_andn2_b64 vcc, exec, s[4:5]
	s_cbranch_vccnz .LBB0_1219
	s_barrier
	s_branch .LBB0_1219

.LBB0_2597:
	v_exp_f32_e32 v150, v126
	v_exp_f32_e32 v152, v122
	v_exp_f32_e32 v151, v127
	v_exp_f32_e32 v156, v124
	v_exp_f32_e32 v157, v125
	v_exp_f32_e32 v153, v123
	v_exp_f32_e32 v154, v128
	v_exp_f32_e32 v155, v129
	s_lshl_b32 s9, s17, 1
	v_pk_add_f32 v[150:151], v[150:151], 1.0 op_sel_hi:[1,0]
	v_pk_add_f32 v[156:157], v[156:157], 1.0 op_sel_hi:[1,0]
	v_pk_add_f32 v[152:153], v[152:153], 1.0 op_sel_hi:[1,0]
	v_lshl_add_u32 v136, s16, 8, v142
	s_or_b32 s16, s9, s56
	v_rcp_f32_e32 v150, v150
	v_rcp_f32_e32 v152, v152
	v_rcp_f32_e32 v151, v151
	v_rcp_f32_e32 v153, v153
	v_rcp_f32_e32 v156, v156
	v_rcp_f32_e32 v157, v157
	s_ashr_i32 s17, s16, 31
	v_pk_add_f32 v[154:155], v[154:155], 1.0 op_sel_hi:[1,0]
	s_lshl_b64 s[16:17], s[16:17], 14
	v_ashrrev_i32_e32 v137, 31, v136
	v_rcp_f32_e32 v154, v154
	v_rcp_f32_e32 v155, v155
	s_mov_b32 s98, 0x1000
	s_mov_b32 s99, 0
	s_mov_b32 s100, 0x4c00
	s_mov_b32 s101, 0
	v_lshl_add_u64 v[148:149], s[16:17], 0, v[136:137]
	v_pk_mul_f32 v[118:119], v[126:127], v[118:119]
	v_pk_mul_f32 v[116:117], v[124:125], v[116:117]
	v_pk_mul_f32 v[114:115], v[122:123], v[114:115]
	v_lshlrev_b64 v[148:149], 7, v[148:149]
	v_pk_mul_f32 v[118:119], v[150:151], v[118:119]
	v_pk_mul_f32 v[122:123], v[156:157], v[116:117]
	v_pk_mul_f32 v[116:117], v[152:153], v[114:115]
	v_lshl_add_u64 v[148:149], v[130:131], 0, v[148:149]
	v_lshl_add_u64 v[252:253], v[148:149], 0, s[98:99]
	v_lshl_add_u64 v[254:255], v[148:149], 0, s[100:101]
	v_pk_mul_f32 v[120:121], v[128:129], v[120:121]
	v_cvt_pk_bf16_f32 v114, v118, v119
	v_cvt_pk_bf16_f32 v116, v116, v117
	v_cvt_pk_bf16_f32 v117, v122, v123
	v_exp_f32_e32 v118, v106
	v_exp_f32_e32 v122, v108
	v_exp_f32_e32 v123, v109
	v_exp_f32_e32 v119, v107
	v_pk_mul_f32 v[120:121], v[154:155], v[120:121]
	v_pk_mul_f32 v[100:101], v[108:109], v[100:101]
	v_cvt_pk_bf16_f32 v115, v120, v121
	global_store_dwordx4 v[148:149], v[114:117], off
	v_exp_f32_e32 v120, v112
	v_exp_f32_e32 v121, v113
	v_exp_f32_e32 v116, v110
	v_exp_f32_e32 v117, v111
	v_pk_add_f32 v[122:123], v[122:123], 1.0 op_sel_hi:[1,0]
	v_pk_add_f32 v[118:119], v[118:119], 1.0 op_sel_hi:[1,0]
	v_rcp_f32_e32 v122, v122
	v_pk_add_f32 v[116:117], v[116:117], 1.0 op_sel_hi:[1,0]
	v_rcp_f32_e32 v118, v118
	v_rcp_f32_e32 v119, v119
	v_rcp_f32_e32 v123, v123
	v_pk_add_f32 v[120:121], v[120:121], 1.0 op_sel_hi:[1,0]
	v_rcp_f32_e32 v116, v116
	v_rcp_f32_e32 v117, v117
	v_rcp_f32_e32 v120, v120
	v_rcp_f32_e32 v121, v121
	v_pk_mul_f32 v[98:99], v[106:107], v[98:99]
	v_pk_mul_f32 v[102:103], v[110:111], v[102:103]
	v_pk_mul_f32 v[106:107], v[122:123], v[100:101]
	v_pk_mul_f32 v[100:101], v[118:119], v[98:99]
	v_pk_mul_f32 v[104:105], v[112:113], v[104:105]
	v_pk_mul_f32 v[102:103], v[116:117], v[102:103]
	v_cvt_pk_bf16_f32 v100, v100, v101
	v_cvt_pk_bf16_f32 v101, v106, v107
	v_pk_mul_f32 v[104:105], v[120:121], v[104:105]
	v_cvt_pk_bf16_f32 v98, v102, v103
	v_exp_f32_e32 v102, v90
	v_cvt_pk_bf16_f32 v99, v104, v105
	global_store_dwordx4 v[252:253], v[98:101], off offset:-2048
	v_exp_f32_e32 v106, v92
	v_exp_f32_e32 v107, v93
	v_exp_f32_e32 v100, v94
	v_exp_f32_e32 v101, v95
	v_exp_f32_e32 v103, v91
	v_exp_f32_e32 v104, v96
	v_exp_f32_e32 v105, v97
	v_pk_add_f32 v[100:101], v[100:101], 1.0 op_sel_hi:[1,0]
	v_pk_add_f32 v[106:107], v[106:107], 1.0 op_sel_hi:[1,0]
	v_pk_add_f32 v[102:103], v[102:103], 1.0 op_sel_hi:[1,0]
	v_rcp_f32_e32 v100, v100
	v_rcp_f32_e32 v102, v102
	v_rcp_f32_e32 v101, v101
	v_rcp_f32_e32 v103, v103
	v_rcp_f32_e32 v106, v106
	v_rcp_f32_e32 v107, v107
	v_pk_add_f32 v[104:105], v[104:105], 1.0 op_sel_hi:[1,0]
	v_rcp_f32_e32 v104, v104
	v_rcp_f32_e32 v105, v105
	v_pk_mul_f32 v[86:87], v[94:95], v[86:87]
	v_pk_mul_f32 v[84:85], v[92:93], v[84:85]
	v_pk_mul_f32 v[82:83], v[90:91], v[82:83]
	v_pk_mul_f32 v[86:87], v[100:101], v[86:87]
	v_pk_mul_f32 v[90:91], v[106:107], v[84:85]
	v_pk_mul_f32 v[84:85], v[102:103], v[82:83]
	v_pk_mul_f32 v[88:89], v[96:97], v[88:89]
	v_cvt_pk_bf16_f32 v82, v86, v87
	v_cvt_pk_bf16_f32 v84, v84, v85
	v_cvt_pk_bf16_f32 v85, v90, v91
	v_exp_f32_e32 v86, v74
	v_exp_f32_e32 v90, v76
	v_exp_f32_e32 v91, v77
	v_exp_f32_e32 v87, v75
	v_pk_mul_f32 v[88:89], v[104:105], v[88:89]
	v_pk_mul_f32 v[68:69], v[76:77], v[68:69]
	v_cvt_pk_bf16_f32 v83, v88, v89
	global_store_dwordx4 v[252:253], v[82:85], off
	v_exp_f32_e32 v88, v80
	v_exp_f32_e32 v89, v81
	v_exp_f32_e32 v84, v78
	v_exp_f32_e32 v85, v79
	v_pk_add_f32 v[90:91], v[90:91], 1.0 op_sel_hi:[1,0]
	v_pk_add_f32 v[86:87], v[86:87], 1.0 op_sel_hi:[1,0]
	v_rcp_f32_e32 v90, v90
	v_pk_add_f32 v[84:85], v[84:85], 1.0 op_sel_hi:[1,0]
	v_rcp_f32_e32 v86, v86
	v_rcp_f32_e32 v87, v87
	v_rcp_f32_e32 v91, v91
	v_pk_add_f32 v[88:89], v[88:89], 1.0 op_sel_hi:[1,0]
	v_rcp_f32_e32 v84, v84
	v_rcp_f32_e32 v85, v85
	v_rcp_f32_e32 v88, v88
	v_rcp_f32_e32 v89, v89
	v_pk_mul_f32 v[66:67], v[74:75], v[66:67]
	v_pk_mul_f32 v[70:71], v[78:79], v[70:71]
	v_pk_mul_f32 v[74:75], v[90:91], v[68:69]
	v_pk_mul_f32 v[68:69], v[86:87], v[66:67]
	v_pk_mul_f32 v[72:73], v[80:81], v[72:73]
	v_pk_mul_f32 v[70:71], v[84:85], v[70:71]
	v_cvt_pk_bf16_f32 v68, v68, v69
	v_cvt_pk_bf16_f32 v69, v74, v75
	v_pk_mul_f32 v[72:73], v[88:89], v[72:73]
	v_cvt_pk_bf16_f32 v66, v70, v71
	v_exp_f32_e32 v70, v58
	v_cvt_pk_bf16_f32 v67, v72, v73
	global_store_dwordx4 v[252:253], v[66:69], off offset:2048
	v_exp_f32_e32 v74, v60
	v_exp_f32_e32 v75, v61
	v_exp_f32_e32 v68, v62
	v_exp_f32_e32 v69, v63
	v_exp_f32_e32 v71, v59
	v_exp_f32_e32 v72, v64
	v_exp_f32_e32 v73, v65
	v_pk_add_f32 v[68:69], v[68:69], 1.0 op_sel_hi:[1,0]
	v_pk_add_f32 v[74:75], v[74:75], 1.0 op_sel_hi:[1,0]
	v_pk_add_f32 v[70:71], v[70:71], 1.0 op_sel_hi:[1,0]
	v_rcp_f32_e32 v68, v68
	v_rcp_f32_e32 v70, v70
	v_rcp_f32_e32 v69, v69
	v_rcp_f32_e32 v71, v71
	v_rcp_f32_e32 v74, v74
	v_rcp_f32_e32 v75, v75
	v_pk_add_f32 v[72:73], v[72:73], 1.0 op_sel_hi:[1,0]
	v_rcp_f32_e32 v72, v72
	v_rcp_f32_e32 v73, v73
	v_pk_mul_f32 v[54:55], v[62:63], v[54:55]
	v_pk_mul_f32 v[52:53], v[60:61], v[52:53]
	v_pk_mul_f32 v[50:51], v[58:59], v[50:51]
	v_pk_mul_f32 v[54:55], v[68:69], v[54:55]
	v_pk_mul_f32 v[58:59], v[74:75], v[52:53]
	v_pk_mul_f32 v[52:53], v[70:71], v[50:51]
	v_pk_mul_f32 v[56:57], v[64:65], v[56:57]
	v_cvt_pk_bf16_f32 v50, v54, v55
	v_cvt_pk_bf16_f32 v52, v52, v53
	v_cvt_pk_bf16_f32 v53, v58, v59
	v_exp_f32_e32 v54, v42
	v_exp_f32_e32 v58, v44
	v_exp_f32_e32 v59, v45
	v_exp_f32_e32 v55, v43
	v_pk_mul_f32 v[56:57], v[72:73], v[56:57]
	v_pk_mul_f32 v[36:37], v[44:45], v[36:37]
	v_cvt_pk_bf16_f32 v51, v56, v57
	global_store_dwordx4 v[254:255], v[50:53], off offset:-3072
	v_exp_f32_e32 v56, v48
	v_exp_f32_e32 v57, v49
	v_exp_f32_e32 v52, v46
	v_exp_f32_e32 v53, v47
	v_pk_add_f32 v[58:59], v[58:59], 1.0 op_sel_hi:[1,0]
	v_pk_add_f32 v[54:55], v[54:55], 1.0 op_sel_hi:[1,0]
	v_rcp_f32_e32 v58, v58
	v_pk_add_f32 v[52:53], v[52:53], 1.0 op_sel_hi:[1,0]
	v_rcp_f32_e32 v54, v54
	v_rcp_f32_e32 v55, v55
	v_rcp_f32_e32 v59, v59
	v_pk_add_f32 v[56:57], v[56:57], 1.0 op_sel_hi:[1,0]
	v_rcp_f32_e32 v52, v52
	v_rcp_f32_e32 v53, v53
	v_rcp_f32_e32 v56, v56
	v_rcp_f32_e32 v57, v57
	v_pk_mul_f32 v[34:35], v[42:43], v[34:35]
	v_pk_mul_f32 v[38:39], v[46:47], v[38:39]
	v_pk_mul_f32 v[42:43], v[58:59], v[36:37]
	v_pk_mul_f32 v[36:37], v[54:55], v[34:35]
	v_pk_mul_f32 v[40:41], v[48:49], v[40:41]
	v_pk_mul_f32 v[38:39], v[52:53], v[38:39]
	v_cvt_pk_bf16_f32 v36, v36, v37
	v_cvt_pk_bf16_f32 v37, v42, v43
	v_pk_mul_f32 v[40:41], v[56:57], v[40:41]
	v_cvt_pk_bf16_f32 v34, v38, v39
	v_exp_f32_e32 v38, v26
	v_cvt_pk_bf16_f32 v35, v40, v41
	global_store_dwordx4 v[254:255], v[34:37], off offset:-1024
	v_exp_f32_e32 v42, v28
	v_exp_f32_e32 v43, v29
	v_exp_f32_e32 v36, v30
	v_exp_f32_e32 v37, v31
	v_exp_f32_e32 v39, v27
	v_exp_f32_e32 v40, v32
	v_exp_f32_e32 v41, v33
	v_pk_add_f32 v[36:37], v[36:37], 1.0 op_sel_hi:[1,0]
	v_pk_add_f32 v[42:43], v[42:43], 1.0 op_sel_hi:[1,0]
	v_pk_add_f32 v[38:39], v[38:39], 1.0 op_sel_hi:[1,0]
	v_pk_add_f32 v[40:41], v[40:41], 1.0 op_sel_hi:[1,0]
	v_rcp_f32_e32 v36, v36
	v_rcp_f32_e32 v38, v38
	v_rcp_f32_e32 v37, v37
	v_rcp_f32_e32 v39, v39
	v_rcp_f32_e32 v42, v42
	v_rcp_f32_e32 v43, v43
	v_rcp_f32_e32 v40, v40
	v_rcp_f32_e32 v41, v41
	v_pk_mul_f32 v[22:23], v[30:31], v[22:23]
	v_pk_mul_f32 v[20:21], v[28:29], v[20:21]
	v_pk_mul_f32 v[18:19], v[26:27], v[18:19]
	v_pk_mul_f32 v[24:25], v[32:33], v[24:25]
	v_pk_mul_f32 v[22:23], v[36:37], v[22:23]
	v_pk_mul_f32 v[26:27], v[42:43], v[20:21]
	v_pk_mul_f32 v[20:21], v[38:39], v[18:19]
	v_pk_mul_f32 v[24:25], v[40:41], v[24:25]
	v_cvt_pk_bf16_f32 v18, v22, v23
	v_cvt_pk_bf16_f32 v20, v20, v21
	v_cvt_pk_bf16_f32 v21, v26, v27
	v_exp_f32_e32 v22, v10
	v_exp_f32_e32 v26, v12
	v_exp_f32_e32 v27, v13
	v_exp_f32_e32 v23, v11
	v_cvt_pk_bf16_f32 v19, v24, v25
	global_store_dwordx4 v[254:255], v[18:21], off offset:1024
	v_exp_f32_e32 v24, v16
	v_exp_f32_e32 v25, v17
	v_exp_f32_e32 v20, v14
	v_exp_f32_e32 v21, v15
	v_pk_add_f32 v[26:27], v[26:27], 1.0 op_sel_hi:[1,0]
	v_pk_add_f32 v[22:23], v[22:23], 1.0 op_sel_hi:[1,0]
	v_pk_add_f32 v[24:25], v[24:25], 1.0 op_sel_hi:[1,0]
	v_pk_add_f32 v[20:21], v[20:21], 1.0 op_sel_hi:[1,0]
	v_rcp_f32_e32 v22, v22
	v_rcp_f32_e32 v23, v23
	v_rcp_f32_e32 v26, v26
	v_rcp_f32_e32 v27, v27
	v_rcp_f32_e32 v20, v20
	v_rcp_f32_e32 v21, v21
	v_rcp_f32_e32 v24, v24
	v_rcp_f32_e32 v25, v25
	v_pk_mul_f32 v[4:5], v[12:13], v[4:5]
	v_pk_mul_f32 v[2:3], v[10:11], v[2:3]
	v_pk_mul_f32 v[8:9], v[16:17], v[8:9]
	v_pk_mul_f32 v[6:7], v[14:15], v[6:7]
	v_pk_mul_f32 v[10:11], v[26:27], v[4:5]
	v_pk_mul_f32 v[4:5], v[22:23], v[2:3]
	s_andn2_b64 vcc, exec, s[2:3]
	s_mov_b64 s[2:3], -1
	v_pk_mul_f32 v[8:9], v[24:25], v[8:9]
	v_pk_mul_f32 v[6:7], v[20:21], v[6:7]
	v_cvt_pk_bf16_f32 v3, v8, v9
	v_cvt_pk_bf16_f32 v4, v4, v5
	v_cvt_pk_bf16_f32 v5, v10, v11
	s_nop 0
	v_cvt_pk_bf16_f32 v2, v6, v7
	global_store_dwordx4 v[254:255], v[2:5], off offset:3072
	s_cbranch_vccnz .LBB0_2590
	s_andn2_b64 vcc, exec, s[4:5]
	s_cbranch_vccnz .LBB0_2589
	s_barrier
	s_branch .LBB0_2589

	.amdhsa_kernel _Z8mega_fwd4Args
		.amdhsa_group_segment_fixed_size 0
		.amdhsa_private_segment_fixed_size 0
		.amdhsa_kernarg_size 456
		.amdhsa_user_sgpr_count 2
		.amdhsa_user_sgpr_dispatch_ptr 0
		.amdhsa_user_sgpr_queue_ptr 0
		.amdhsa_user_sgpr_kernarg_segment_ptr 1
		.amdhsa_user_sgpr_dispatch_id 0
		.amdhsa_user_sgpr_kernarg_preload_length 0
		.amdhsa_user_sgpr_kernarg_preload_offset 0
		.amdhsa_user_sgpr_private_segment_size 0
		.amdhsa_uses_dynamic_stack 0
		.amdhsa_enable_private_segment 0
		.amdhsa_system_sgpr_workgroup_id_x 1
		.amdhsa_system_sgpr_workgroup_id_y 0
		.amdhsa_system_sgpr_workgroup_id_z 0
		.amdhsa_system_sgpr_workgroup_info 0
		.amdhsa_system_vgpr_workitem_id 0
		.amdhsa_next_free_vgpr 256
		.amdhsa_next_free_sgpr 102
		.amdhsa_accum_offset 256
		.amdhsa_reserve_vcc 1
		.amdhsa_float_round_mode_32 0
		.amdhsa_float_round_mode_16_64 0
		.amdhsa_float_denorm_mode_32 3
		.amdhsa_float_denorm_mode_16_64 3
		.amdhsa_dx10_clamp 1
		.amdhsa_ieee_mode 1
		.amdhsa_fp16_overflow 0
		.amdhsa_tg_split 0
		.amdhsa_exception_fp_ieee_invalid_op 0
		.amdhsa_exception_fp_denorm_src 0
		.amdhsa_exception_fp_ieee_div_zero 0
		.amdhsa_exception_fp_ieee_overflow 0
		.amdhsa_exception_fp_ieee_underflow 0
		.amdhsa_exception_fp_ieee_inexact 0
		.amdhsa_exception_int_div_zero 0
	.end_amdhsa_kernel

amdhsa.kernels:
  - .agpr_count:     0
    .args:
      - .offset:         0
        .size:           200
        .value_kind:     by_value
      - .offset:         200
        .size:           4
        .value_kind:     hidden_block_count_x
      - .offset:         204
        .size:           4
        .value_kind:     hidden_block_count_y
      - .offset:         208
        .size:           4
        .value_kind:     hidden_block_count_z
      - .offset:         212
        .size:           2
        .value_kind:     hidden_group_size_x
      - .offset:         214
        .size:           2
        .value_kind:     hidden_group_size_y
      - .offset:         216
        .size:           2
        .value_kind:     hidden_group_size_z
      - .offset:         218
        .size:           2
        .value_kind:     hidden_remainder_x
      - .offset:         220
        .size:           2
        .value_kind:     hidden_remainder_y
      - .offset:         222
        .size:           2
        .value_kind:     hidden_remainder_z
      - .offset:         240
        .size:           8
        .value_kind:     hidden_global_offset_x
      - .offset:         248
        .size:           8
        .value_kind:     hidden_global_offset_y
      - .offset:         256
        .size:           8
        .value_kind:     hidden_global_offset_z
      - .offset:         264
        .size:           2
        .value_kind:     hidden_grid_dims
      - .offset:         320
        .size:           4
        .value_kind:     hidden_dynamic_lds_size
    .group_segment_fixed_size: 0
    .kernarg_segment_align: 8
    .kernarg_segment_size: 456
    .language:       OpenCL C
    .language_version:
      - 2
      - 0
    .max_flat_workgroup_size: 512
    .name:           _Z8mega_fwd4Args
    .private_segment_fixed_size: 0
    .sgpr_count:     108
    .sgpr_spill_count: 22
    .symbol:         _Z8mega_fwd4Args.kd
    .uniform_work_group_size: 1
    .uses_dynamic_stack: false
    .vgpr_count:     256
    .vgpr_spill_count: 0
    .wavefront_size: 64
